# P3 prologue (lambda chain + subln_g loads) overlapped with grid-barrier-3 wait by waves 1-7; wave 0 receives lam/sg via LDS handoff
# baseline (speedup 1.0000x reference)
.LBB0_613:
	s_or_b64 exec, exec, s[4:5]
	s_mov_b32 s8, s33
	s_mov_b32 s4, -1
	s_waitcnt lgkmcnt(0)
	s_mov_b32 s9, s2
	v_mbcnt_lo_u32_b32 v0, s4, 0
	v_mbcnt_hi_u32_b32 v0, s4, v0
	v_lshl_add_u32 v0, s8, 6, v0
	s_mov_b32 s12, s3
	s_and_b32 s4, s12, 7
	s_cmp_lg_u32 s4, 0
	s_mov_b32 s19, 0
	s_cbranch_scc1 .LBB0_615
	s_ashr_i32 s5, s9, 31
	s_lshr_b32 s5, s5, 29
	s_add_i32 s5, s9, s5
	s_ashr_i32 s6, s5, 3
	s_and_b32 s5, s5, -8
	s_ashr_i32 s4, s12, 3
	s_sub_i32 s5, s9, s5
	s_mul_i32 s4, s5, s4
	s_add_i32 s9, s4, s6

.LBB0_618:
	s_load_dwordx8 s[24:31], s[6:7], 0x20
	v_and_b32_e32 v0, 63, v0
	v_lshlrev_b32_e32 v1, 2, v0
	s_waitcnt lgkmcnt(0)
	s_cmp_eq_u32 s33, 0
	s_cbranch_scc1 .Lp3_skipA
	global_load_dword v2, v1, s[24:25]
	global_load_dword v3, v1, s[26:27]
	global_load_dword v4, v1, s[28:29]
	global_load_dword v5, v1, s[30:31]
	s_waitcnt vmcnt(2)
	v_mul_f32_e32 v1, v2, v3
	ds_swizzle_b32 v1, v1 offset:swizzle(SWAP,1)
	s_waitcnt vmcnt(0)
	v_mul_f32_e32 v6, v4, v5
	ds_swizzle_b32 v6, v6 offset:swizzle(SWAP,1)
	s_waitcnt lgkmcnt(1)
	v_fmac_f32_e32 v1, v2, v3
	ds_swizzle_b32 v2, v1 offset:swizzle(SWAP,2)
	s_waitcnt lgkmcnt(1)
	v_fmac_f32_e32 v6, v4, v5
	ds_swizzle_b32 v3, v6 offset:swizzle(SWAP,2)
	s_waitcnt lgkmcnt(1)
	v_add_f32_e32 v1, v1, v2
	s_waitcnt lgkmcnt(0)
	v_add_f32_e32 v2, v6, v3
	ds_swizzle_b32 v3, v1 offset:swizzle(SWAP,4)
	ds_swizzle_b32 v4, v2 offset:swizzle(SWAP,4)
	s_waitcnt lgkmcnt(1)
	v_add_f32_e32 v1, v1, v3
	s_waitcnt lgkmcnt(0)
	v_add_f32_e32 v2, v2, v4
	ds_swizzle_b32 v3, v1 offset:swizzle(SWAP,8)
	ds_swizzle_b32 v4, v2 offset:swizzle(SWAP,8)
	s_waitcnt lgkmcnt(1)
	v_add_f32_e32 v1, v1, v3
	s_waitcnt lgkmcnt(0)
	v_add_f32_e32 v2, v2, v4
	ds_swizzle_b32 v3, v1 offset:swizzle(SWAP,16)
	ds_swizzle_b32 v4, v2 offset:swizzle(SWAP,16)
	s_waitcnt lgkmcnt(1)
	v_add_f32_e32 v3, v1, v3
	s_waitcnt lgkmcnt(0)
	v_add_f32_e32 v1, v2, v4
	v_mov_b32_e32 v4, v3
	v_mov_b32_e32 v2, v1
	s_nop 0
	v_permlane32_swap_b32_e32 v3, v4
	v_permlane32_swap_b32_e32 v1, v2
.Lp3_skipA:
	s_add_i32 s25, s9, s8
	s_load_dwordx2 s[6:7], s[6:7], 0x40
	v_lshlrev_b32_e32 v5, 5, v0
	v_and_b32_e32 v5, 0x1e0, v5
	v_lshlrev_b32_e32 v12, 3, v0
	v_add_f32_e32 v0, v3, v4
	s_waitcnt lgkmcnt(0)
	s_cmp_eq_u32 s33, 0
	s_cbranch_scc1 .Lp3_skipB
	global_load_dwordx4 v[6:9], v5, s[6:7]
	global_load_dwordx4 v[20:23], v5, s[6:7] offset:16
.Lp3_skipB:
	s_mov_b32 s8, 0x3fb8aa3b
	v_add_f32_e32 v1, v1, v2
	v_mul_f32_e32 v2, 0x3fb8aa3b, v0
	v_mul_f32_e32 v4, 0x3fb8aa3b, v1
	v_fma_f32 v5, v0, s8, -v2
	v_rndne_f32_e32 v10, v2
	v_fma_f32 v11, v1, s8, -v4
	v_rndne_f32_e32 v14, v4
	v_fmac_f32_e32 v5, 0x32a5705f, v0
	v_sub_f32_e32 v2, v2, v10
	v_fmac_f32_e32 v11, 0x32a5705f, v1
	v_sub_f32_e32 v4, v4, v14
	v_add_f32_e32 v2, v2, v5
	v_cvt_i32_f32_e32 v10, v10
	v_add_f32_e32 v4, v4, v11
	v_exp_f32_e32 v2, v2
	v_cvt_i32_f32_e32 v14, v14
	v_exp_f32_e32 v4, v4
	s_mov_b32 s24, 0xc2ce8ed0
	s_add_u32 s6, s4, 0x2000000
	v_ldexp_f32 v2, v2, v10
	v_cmp_ngt_f32_e32 vcc, s24, v0
	s_mov_b32 s26, 0x42b17218
	s_addc_u32 s7, s5, 0
	v_ldexp_f32 v4, v4, v14
	v_cndmask_b32_e32 v2, 0, v2, vcc
	v_cmp_ngt_f32_e32 vcc, s24, v1
	v_mov_b32_e32 v3, 0x7f800000
	s_add_u32 s8, s4, 0x3000000
	v_cndmask_b32_e32 v4, 0, v4, vcc
	v_cmp_nlt_f32_e32 vcc, s26, v0
	s_addc_u32 s9, s5, 0
	s_add_u32 s12, s4, 0x7000000
	v_cndmask_b32_e32 v0, v3, v2, vcc
	v_cmp_nlt_f32_e32 vcc, s26, v1
	s_addc_u32 s13, s5, 0
	s_mov_b32 s18, 0x3f4ccccd
	v_cndmask_b32_e32 v1, v3, v4, vcc
	v_sub_f32_e32 v0, v0, v1
	s_add_u32 s16, s4, 0x4000000
	v_add_f32_e32 v14, 0x3e4ccccd, v0
	s_mov_b32 s22, 0xffff0000
	v_mov_b32_e32 v13, 0x3727c5ac
	s_mov_b32 s23, 0xf800000
	v_mov_b32_e32 v26, 0x260
	s_addc_u32 s17, s5, 0
	v_mov_b32_e32 v15, v14
	s_waitcnt vmcnt(1)
	v_mov_b32_e32 v0, v6
	v_mov_b32_e32 v1, v8
	v_mov_b32_e32 v8, v7
	s_waitcnt vmcnt(0)
	v_mov_b32_e32 v2, v20
	v_mov_b32_e32 v3, v22
	v_mov_b32_e32 v22, v21
	v_pk_mul_f32 v[16:17], v[0:1], s[18:19] op_sel_hi:[1,0]
	v_pk_mul_f32 v[18:19], v[8:9], s[18:19] op_sel_hi:[1,0]
	v_pk_mul_f32 v[20:21], v[2:3], s[18:19] op_sel_hi:[1,0]
	v_pk_mul_f32 v[22:23], v[22:23], s[18:19] op_sel_hi:[1,0]
	s_movk_i32 s18, 0x7fff
	v_lshrrev_b32_e32 v27, 1, v12
	s_cmp_eq_u32 s33, 1
	s_cbranch_scc0 .Lp3_nowr
	ds_write_b32 v27, v14
	ds_write_b32 v27, v16 offset:256
	ds_write_b32 v27, v17 offset:512
	ds_write_b32 v27, v18 offset:768
	ds_write_b32 v27, v19 offset:1024
	ds_write_b32 v27, v20 offset:1280
	ds_write_b32 v27, v21 offset:1536
	ds_write_b32 v27, v22 offset:1792
	ds_write_b32 v27, v23 offset:2048
.Lp3_nowr:
	s_waitcnt lgkmcnt(0)
	s_barrier
	s_cmp_eq_u32 s33, 0
	s_cbranch_scc0 .Lp3_nord
	ds_read_b32 v14, v27
	ds_read_b32 v16, v27 offset:256
	ds_read_b32 v17, v27 offset:512
	ds_read_b32 v18, v27 offset:768
	ds_read_b32 v19, v27 offset:1024
	ds_read_b32 v20, v27 offset:1280
	ds_read_b32 v21, v27 offset:1536
	ds_read_b32 v22, v27 offset:1792
	ds_read_b32 v23, v27 offset:2048
	s_waitcnt lgkmcnt(0)
	v_mov_b32_e32 v15, v14
.Lp3_nord:
	s_cmp_ge_i32 s25, s21
	s_cbranch_scc1 .LBB0_623
	s_branch .LBB0_621
